# grid barrier: 16 replicated release lines (16 pollers each) instead of 4, group-last arrivers bump all 16
# baseline (speedup 1.0000x reference)
; DI void fast_grid_barrier(unsigned* ctr, unsigned target) {
;     asm volatile("s_waitcnt vmcnt(0)" ::: "memory");
;     __syncthreads();
;     if (threadIdx.x == 0) {
;         __builtin_amdgcn_fence(__ATOMIC_RELEASE, "agent");
;         asm volatile("s_waitcnt vmcnt(0)" ::: "memory");
;         __hip_atomic_fetch_add(ctr, 1u, __ATOMIC_RELAXED, __HIP_MEMORY_SCOPE_AGENT);
;         while (__hip_atomic_load(ctr, __ATOMIC_RELAXED, __HIP_MEMORY_SCOPE_AGENT) < target) __builtin_amdgcn_s_sleep(1);
;         __builtin_amdgcn_fence(__ATOMIC_ACQUIRE, "agent");
;         asm volatile("s_waitcnt vmcnt(0)" ::: "memory");
;     }
;     __syncthreads();
; }
.LBB0_4:
	s_cmp_le_i32 s70, s12
	s_cbranch_scc1 .LBB0_26
	v_readlane_b32 s0, v255, 4
	s_cmp_lg_u32 s70, s0
	s_mov_b64 s[0:1], -1
	s_waitcnt vmcnt(0)
	v_readlane_b32 s0, v255, 11
	s_add_i32 s4, s0, 1
	s_barrier
	s_mov_b64 s[0:1], exec
	v_readlane_b32 s6, v255, 12
	v_readlane_b32 s7, v255, 13
	s_and_b64 s[6:7], s[0:1], s[6:7]
	s_mov_b64 exec, s[6:7]
	s_cbranch_execz .LBB0_12
	s_cmp_lg_u32 s4, 1
	s_cbranch_scc1 .Lgb_arrive
	s_cmp_lg_u32 s2, 0
	s_cbranch_scc1 .Lgb_arrive
	v_mov_b32_e32 v1, 0x1000
	global_store_dword v1, v165, s[14:15]
	global_store_dword v1, v165, s[14:15] offset:256
	global_store_dword v1, v165, s[14:15] offset:512
	global_store_dword v1, v165, s[14:15] offset:768
	global_store_dword v1, v165, s[14:15] offset:1024
	global_store_dword v1, v165, s[14:15] offset:1280
	global_store_dword v1, v165, s[14:15] offset:1536
	global_store_dword v1, v165, s[14:15] offset:1792
	global_store_dword v1, v165, s[14:15] offset:2048
	global_store_dword v1, v165, s[14:15] offset:2304
	global_store_dword v1, v165, s[14:15] offset:2560
	global_store_dword v1, v165, s[14:15] offset:2816
	global_store_dword v1, v165, s[14:15] offset:3072
	global_store_dword v1, v165, s[14:15] offset:3328
	global_store_dword v1, v165, s[14:15] offset:3584
	v_mov_b32_e32 v1, 0x1f00
	global_store_dword v1, v165, s[14:15]
	global_store_dword v1, v165, s[14:15] offset:256
	global_store_dword v1, v165, s[14:15] offset:512
	global_store_dword v1, v165, s[14:15] offset:768
	global_store_dword v1, v165, s[14:15] offset:1024
.Lgb_arrive:
	buffer_wbl2 sc1
	s_waitcnt vmcnt(0)
	v_mov_b32_e32 v0, 1
	s_cmp_eq_u32 s4, 1
	s_cbranch_scc1 .Lgb_first
	s_and_b32 s5, s2, 3
	s_sub_i32 s9, s72, s5
	s_add_i32 s9, s9, 3
	s_lshr_b32 s9, s9, 2
	s_lshl_b32 s8, s5, 8
	s_add_i32 s8, s8, 0x2000
	v_mov_b32_e32 v1, s8
	global_atomic_add v2, v1, v0, s[14:15] sc0
	s_add_i32 s5, s4, -1
	s_mul_i32 s9, s9, s5
	s_lshl_b32 s5, s5, 2
	s_bfe_u32 s8, s2, 0x40002
	s_lshl_b32 s8, s8, 8
	s_add_i32 s8, s8, 0x1000
	s_waitcnt vmcnt(0)
	v_add_u32_e32 v2, 1, v2
	v_cmp_eq_u32_e32 vcc, s9, v2
	s_cbranch_vccz .Lgb_poll2
	v_mov_b32_e32 v1, 0x1000
	global_atomic_add v1, v0, s[14:15]
	global_atomic_add v1, v0, s[14:15] offset:256
	global_atomic_add v1, v0, s[14:15] offset:512
	global_atomic_add v1, v0, s[14:15] offset:768
	global_atomic_add v1, v0, s[14:15] offset:1024
	global_atomic_add v1, v0, s[14:15] offset:1280
	global_atomic_add v1, v0, s[14:15] offset:1536
	global_atomic_add v1, v0, s[14:15] offset:1792
	global_atomic_add v1, v0, s[14:15] offset:2048
	global_atomic_add v1, v0, s[14:15] offset:2304
	global_atomic_add v1, v0, s[14:15] offset:2560
	global_atomic_add v1, v0, s[14:15] offset:2816
	global_atomic_add v1, v0, s[14:15] offset:3072
	global_atomic_add v1, v0, s[14:15] offset:3328
	global_atomic_add v1, v0, s[14:15] offset:3584
	v_mov_b32_e32 v1, 0x1f00
	global_atomic_add v1, v0, s[14:15]

; DI void fast_grid_barrier(unsigned* ctr, unsigned target) {
;     asm volatile("s_waitcnt vmcnt(0)" ::: "memory");
;     __syncthreads();
;     if (threadIdx.x == 0) {
;         __builtin_amdgcn_fence(__ATOMIC_RELEASE, "agent");
;         asm volatile("s_waitcnt vmcnt(0)" ::: "memory");
;         __hip_atomic_fetch_add(ctr, 1u, __ATOMIC_RELAXED, __HIP_MEMORY_SCOPE_AGENT);
;         while (__hip_atomic_load(ctr, __ATOMIC_RELAXED, __HIP_MEMORY_SCOPE_AGENT) < target) __builtin_amdgcn_s_sleep(1);
;         __builtin_amdgcn_fence(__ATOMIC_ACQUIRE, "agent");
;         asm volatile("s_waitcnt vmcnt(0)" ::: "memory");
;     }
;     __syncthreads();
; }
.Lgb_first:
	s_and_b32 s5, s2, 3
	s_sub_i32 s9, s72, s5
	s_add_i32 s9, s9, 3
	s_lshr_b32 s9, s9, 2
	s_lshl_b32 s8, s5, 5
	s_add_i32 s8, s8, 0x80
	v_mov_b32_e32 v1, s8
	global_atomic_add v2, v1, v0, s[14:15] sc0
	s_mul_i32 s9, s9, s4
	s_lshl_b32 s5, s4, 2
	s_waitcnt vmcnt(0)
	v_add_u32_e32 v2, 1, v2
	v_cmp_eq_u32_e32 vcc, s9, v2
	s_cbranch_vccz .Lgb_poll
	global_atomic_add v165, v0, s[14:15]
